# ATTN compressed-branch passes: bias-table addresses formed in the scaled byte domain (3 VALU per entry instead of 4, 64 instructions fewer per block pair)
# speedup vs baseline: 1.0168x; 1.0041x over previous
.Lfa_btab_skip:
	s_lshl_b32 s40, s8, 6
	s_lshl_b64 s[0:1], s[50:51], 16
	s_add_u32 s0, s73, s0
	s_addc_u32 s1, s19, s1
	s_lshl_b32 s2, s8, 7
	s_add_u32 s0, s0, s2
	s_addc_u32 s1, s1, 0
	v_mov_b32_e32 v121, v32
	v_lshl_add_u64 v[0:1], s[0:1], 0, v[120:121]
	s_mov_b64 s[0:1], 0x200000
	v_lshlrev_b64 v[4:5], 1, v[114:115]
	v_lshl_add_u64 v[2:3], v[0:1], 0, s[0:1]
	v_lshl_add_u64 v[6:7], v[0:1], 0, v[4:5]
	v_lshl_add_u64 v[4:5], v[2:3], 0, v[4:5]
	global_load_dwordx4 v[16:19], v[6:7], off
	global_load_dwordx4 v[20:23], v[4:5], off
	v_lshl_add_u64 v[0:1], v[0:1], 0, v[118:119]
	global_load_dwordx4 v[24:27], v[0:1], off
	v_lshl_add_u64 v[0:1], v[2:3], 0, v[118:119]
	global_load_dwordx4 v[28:31], v[0:1], off
	s_lshl_b32 s2, s40, 1
	s_mul_i32 s0, s50, 0x600000
	s_mul_hi_i32 s1, s50, 0x600000
	s_add_u32 s0, s24, s0
	s_addc_u32 s1, s25, s1
	s_add_u32 s0, s0, s2
	s_addc_u32 s1, s1, 0
	v_lshl_add_u64 v[252:253], s[0:1], 0, v[112:113]
	v_lshl_add_u64 v[252:253], v[252:253], 0, v[120:121]
	global_load_dwordx4 v[236:239], v[252:253], off offset:1024
	global_load_dwordx4 v[240:243], v[252:253], off offset:1536
	v_mov_b32_e32 v33, v32
	s_cmp_gt_i32 s45, 15
	v_mov_b32_e32 v34, v32
	v_mov_b32_e32 v35, v32
	v_mov_b32_e32 v36, v32
	v_mov_b32_e32 v37, v32
	v_mov_b32_e32 v38, v32
	v_mov_b32_e32 v39, v32
	v_mov_b32_e32 v40, v32
	v_mov_b32_e32 v41, v32
	v_mov_b32_e32 v42, v32
	v_mov_b32_e32 v43, v32
	v_mov_b32_e32 v44, v32
	v_mov_b32_e32 v45, v32
	v_mov_b32_e32 v46, v32
	v_mov_b32_e32 v47, v32
	v_mov_b64_e32 v[0:1], v[32:33]
	s_cselect_b64 s[30:31], -1, 0
	s_add_i32 s101, s69, -4
	s_cmp_lt_i32 s45, 16
	s_mov_b32 s3, 0
	v_subrev_u32_e32 v66, 31, v130
	v_lshl_add_u32 v253, v209, 2, s69
	v_lshl_add_u32 v252, v66, 2, s69
	v_mov_b32_e32 v67, 0
	v_mov_b32_e32 v48, 0xff800000
	s_mov_b64 s[34:35], -1
	v_mov_b64_e32 v[2:3], v[34:35]
	v_mov_b64_e32 v[4:5], v[36:37]
	v_mov_b64_e32 v[6:7], v[38:39]
	v_mov_b64_e32 v[8:9], v[40:41]
	v_mov_b64_e32 v[10:11], v[42:43]
	v_mov_b64_e32 v[12:13], v[44:45]
	v_mov_b64_e32 v[14:15], v[46:47]
	s_cselect_b64 s[0:1], -1, 0
	s_waitcnt vmcnt(5)
	ds_write_b128 v195, v[16:19]
	s_waitcnt vmcnt(3)
	ds_write_b128 v195, v[24:27] offset:9216
	ds_write_b128 v195, v[20:23] offset:18432
	s_waitcnt vmcnt(2)
	ds_write_b128 v195, v[28:31] offset:27648
	v_mov_b64_e32 v[16:17], v[32:33]
	v_mov_b64_e32 v[18:19], v[34:35]
	v_mov_b64_e32 v[20:21], v[36:37]
	v_mov_b64_e32 v[22:23], v[38:39]
	v_mov_b64_e32 v[24:25], v[40:41]
	v_mov_b64_e32 v[26:27], v[42:43]
	v_mov_b64_e32 v[28:29], v[44:45]
	v_mov_b64_e32 v[30:31], v[46:47]
	s_waitcnt lgkmcnt(0)
	s_barrier
.LBB0_1285:
	s_mul_i32 s2, s3, 0x2400
	v_add_u32_e32 v33, s2, v156
	v_add_u32_e32 v42, v33, v157
	ds_read_b128 v[34:37], v42
	ds_read_b128 v[38:41], v42 offset:32
	v_add_u32_e32 v33, v33, v158
	v_mov_b32_e32 v68, v48
	s_lshl_b32 s3, s3, 6
	s_waitcnt lgkmcnt(1)
	v_mfma_f32_32x32x16_bf16 v[50:65], v[34:37], v[80:83], 0
	ds_read_b128 v[34:37], v42 offset:64
	s_waitcnt lgkmcnt(1)
	v_mfma_f32_32x32x16_bf16 v[50:65], v[38:41], v[84:87], v[50:65]
	s_waitcnt lgkmcnt(0)
	v_mfma_f32_32x32x16_bf16 v[50:65], v[34:37], v[88:91], v[50:65]
	ds_read_b128 v[34:37], v42 offset:96
	s_waitcnt lgkmcnt(0)
	v_mfma_f32_32x32x16_bf16 v[50:65], v[34:37], v[92:95], v[50:65]
	ds_read_b128 v[34:37], v33
	ds_read_b128 v[70:73], v33 offset:32
	s_waitcnt lgkmcnt(1)
	v_mfma_f32_32x32x16_bf16 v[34:49], v[34:37], v[80:83], 0
	s_waitcnt lgkmcnt(0)
	v_mfma_f32_32x32x16_bf16 v[34:49], v[70:73], v[84:87], v[34:49]
	ds_read_b128 v[70:73], v33 offset:64
	s_waitcnt lgkmcnt(0)
	v_mfma_f32_32x32x16_bf16 v[34:49], v[70:73], v[88:91], v[34:49]
	ds_read_b128 v[70:73], v33 offset:96
	v_subrev_u32_e32 v33, s3, v159
	v_lshl_add_u32 v33, v33, 6, v252
	v_med3_i32 v33, v33, s101, v253
	ds_read_b32 v69, v33 offset:256
	v_xad_u32 v33, s3, -1, v159
	v_lshl_add_u32 v33, v33, 6, v252
	v_med3_i32 v33, v33, s101, v253
	s_waitcnt lgkmcnt(1)
	v_mfma_f32_32x32x16_bf16 v[34:49], v[70:73], v[92:95], v[34:49]
	ds_read_b32 v70, v33 offset:256
	v_subrev_u32_e32 v33, s3, v160
	v_lshl_add_u32 v33, v33, 6, v252
	v_med3_i32 v33, v33, s101, v253
	ds_read_b32 v71, v33 offset:256
	v_subrev_u32_e32 v33, s3, v161
	v_lshl_add_u32 v33, v33, 6, v252
	v_med3_i32 v33, v33, s101, v253
	ds_read_b32 v72, v33 offset:256
	v_subrev_u32_e32 v33, s3, v162
	v_lshl_add_u32 v33, v33, 6, v252
	v_med3_i32 v33, v33, s101, v253
	ds_read_b32 v75, v33 offset:256
	v_subrev_u32_e32 v33, s3, v163
	v_lshl_add_u32 v33, v33, 6, v252
	v_med3_i32 v33, v33, s101, v253
	ds_read_b32 v73, v33 offset:256
	v_subrev_u32_e32 v33, s3, v164
	v_lshl_add_u32 v33, v33, 6, v252
	v_med3_i32 v33, v33, s101, v253
	ds_read_b32 v74, v33 offset:256
	v_subrev_u32_e32 v33, s3, v165
	v_lshl_add_u32 v33, v33, 6, v252
	v_med3_i32 v33, v33, s101, v253
	ds_read_b32 v76, v33 offset:256
	s_waitcnt lgkmcnt(7)
	v_fmac_f32_e32 v69, 0x3fb8aa3b, v50
	s_waitcnt lgkmcnt(6)
	v_fmac_f32_e32 v70, 0x3fb8aa3b, v51
	v_max3_f32 v33, v69, s70, v70
	s_waitcnt lgkmcnt(5)
	v_fmac_f32_e32 v71, 0x3fb8aa3b, v52
	s_waitcnt lgkmcnt(4)
	v_fmac_f32_e32 v72, 0x3fb8aa3b, v53
	v_max3_f32 v33, v33, v71, v72
	s_waitcnt lgkmcnt(3)
	v_fmac_f32_e32 v75, 0x3fb8aa3b, v54
	s_waitcnt lgkmcnt(2)
	v_fmac_f32_e32 v73, 0x3fb8aa3b, v55
	v_max3_f32 v33, v33, v75, v73
	s_waitcnt lgkmcnt(1)
	v_fmac_f32_e32 v74, 0x3fb8aa3b, v56
	s_waitcnt lgkmcnt(0)
	v_fmac_f32_e32 v76, 0x3fb8aa3b, v57
	v_max3_f32 v33, v33, v74, v76
	v_subrev_u32_e32 v50, s3, v166
	v_subrev_u32_e32 v51, s3, v167
	v_subrev_u32_e32 v53, s3, v169
	v_subrev_u32_e32 v55, s3, v171
	v_lshl_add_u32 v50, v50, 6, v252
	v_lshl_add_u32 v51, v51, 6, v252
	v_subrev_u32_e32 v52, s3, v168
	v_lshl_add_u32 v53, v53, 6, v252
	v_subrev_u32_e32 v54, s3, v170
	v_lshl_add_u32 v55, v55, 6, v252
	v_subrev_u32_e32 v56, s3, v172
	v_subrev_u32_e32 v57, s3, v173
	v_med3_i32 v50, v50, s101, v253
	v_med3_i32 v51, v51, s101, v253
	v_lshl_add_u32 v52, v52, 6, v252
	v_med3_i32 v53, v53, s101, v253
	v_lshl_add_u32 v54, v54, 6, v252
	v_med3_i32 v55, v55, s101, v253
	v_lshl_add_u32 v56, v56, 6, v252
	v_lshl_add_u32 v57, v57, 6, v252
	v_med3_i32 v52, v52, s101, v253
	v_med3_i32 v54, v54, s101, v253
	v_med3_i32 v56, v56, s101, v253
	v_med3_i32 v57, v57, s101, v253
	v_mov_b32_e32 v97, v57
	ds_read_b32 v96, v50 offset:256
	ds_read_b32 v79, v51 offset:256
	ds_read_b32 v78, v52 offset:256
	ds_read_b32 v77, v53 offset:256
	ds_read_b32 v57, v54 offset:256
	ds_read_b32 v55, v55 offset:256
	ds_read_b32 v53, v56 offset:256
	ds_read_b32 v51, v97 offset:256
	s_waitcnt lgkmcnt(7)
	v_fmac_f32_e32 v96, 0x3fb8aa3b, v58
	s_waitcnt lgkmcnt(6)
	v_fmac_f32_e32 v79, 0x3fb8aa3b, v59
	v_max3_f32 v33, v33, v96, v79
	s_waitcnt lgkmcnt(5)
	v_fmac_f32_e32 v78, 0x3fb8aa3b, v60
	s_waitcnt lgkmcnt(4)
	v_fmac_f32_e32 v77, 0x3fb8aa3b, v61
	v_max3_f32 v33, v33, v78, v77
	s_waitcnt lgkmcnt(3)
	v_fmac_f32_e32 v57, 0x3fb8aa3b, v62
	s_waitcnt lgkmcnt(2)
	v_fmac_f32_e32 v55, 0x3fb8aa3b, v63
	v_max3_f32 v33, v33, v57, v55
	s_waitcnt lgkmcnt(1)
	v_fmac_f32_e32 v53, 0x3fb8aa3b, v64
	s_waitcnt lgkmcnt(0)
	v_fmac_f32_e32 v51, 0x3fb8aa3b, v65
	v_max3_f32 v33, v33, v53, v51
	v_subrev_u32_e32 v58, s3, v178
	v_lshl_add_u32 v58, v58, 6, v252
	v_med3_i32 v58, v58, s101, v253
	v_mov_b32_e32 v61, v58
	v_subrev_u32_e32 v58, s3, v179
	v_lshl_add_u32 v58, v58, 6, v252
	v_med3_i32 v58, v58, s101, v253
	v_mov_b32_e32 v63, v58
	v_subrev_u32_e32 v58, s3, v180
	v_lshl_add_u32 v58, v58, 6, v252
	v_subrev_u32_e32 v50, s3, v174
	v_subrev_u32_e32 v52, s3, v175
	v_subrev_u32_e32 v54, s3, v176
	v_subrev_u32_e32 v56, s3, v177
	v_med3_i32 v58, v58, s101, v253
	v_lshl_add_u32 v50, v50, 6, v252
	v_lshl_add_u32 v52, v52, 6, v252
	v_lshl_add_u32 v54, v54, 6, v252
	v_lshl_add_u32 v56, v56, 6, v252
	v_mov_b32_e32 v64, v58
	v_subrev_u32_e32 v58, s3, v181
	v_med3_i32 v50, v50, s101, v253
	v_med3_i32 v52, v52, s101, v253
	v_med3_i32 v54, v54, s101, v253
	v_med3_i32 v56, v56, s101, v253
	v_lshl_add_u32 v58, v58, 6, v252
	v_med3_i32 v58, v58, s101, v253
	v_mov_b32_e32 v65, v58
	ds_read_b32 v62, v50 offset:256
	ds_read_b32 v60, v52 offset:256
	ds_read_b32 v59, v54 offset:256
	ds_read_b32 v58, v56 offset:256
	ds_read_b32 v56, v61 offset:256
	ds_read_b32 v54, v63 offset:256
	ds_read_b32 v52, v64 offset:256
	ds_read_b32 v50, v65 offset:256
	s_waitcnt lgkmcnt(7)
	v_fmac_f32_e32 v62, 0x3fb8aa3b, v34
	s_waitcnt lgkmcnt(6)
	v_fmac_f32_e32 v60, 0x3fb8aa3b, v35
	v_max3_f32 v33, v33, v62, v60
	s_waitcnt lgkmcnt(5)
	v_fmac_f32_e32 v59, 0x3fb8aa3b, v36
	s_waitcnt lgkmcnt(4)
	v_fmac_f32_e32 v58, 0x3fb8aa3b, v37
	v_max3_f32 v33, v33, v59, v58
	s_waitcnt lgkmcnt(3)
	v_fmac_f32_e32 v56, 0x3fb8aa3b, v38
	s_waitcnt lgkmcnt(2)
	v_fmac_f32_e32 v54, 0x3fb8aa3b, v39
	v_max3_f32 v33, v33, v56, v54
	s_waitcnt lgkmcnt(1)
	v_fmac_f32_e32 v52, 0x3fb8aa3b, v40
	s_waitcnt lgkmcnt(0)
	v_fmac_f32_e32 v50, 0x3fb8aa3b, v41
	v_max3_f32 v33, v33, v52, v50
	v_subrev_u32_e32 v39, s3, v187
	v_lshl_add_u32 v39, v39, 6, v252
	v_med3_i32 v39, v39, s101, v253
	v_mov_b32_e32 v63, v39
	v_subrev_u32_e32 v39, s3, v189
	v_lshl_add_u32 v39, v39, 6, v252
	v_subrev_u32_e32 v34, s3, v182
	v_subrev_u32_e32 v35, s3, v183
	v_subrev_u32_e32 v36, s3, v184
	v_subrev_u32_e32 v37, s3, v185
	v_subrev_u32_e32 v38, s3, v186
	v_med3_i32 v39, v39, s101, v253
	v_lshl_add_u32 v34, v34, 6, v252
	v_lshl_add_u32 v35, v35, 6, v252
	v_lshl_add_u32 v36, v36, 6, v252
	v_lshl_add_u32 v37, v37, 6, v252
	v_lshl_add_u32 v38, v38, 6, v252
	v_mov_b32_e32 v64, v39
	v_subrev_u32_e32 v39, s3, v190
	v_med3_i32 v34, v34, s101, v253
	v_med3_i32 v35, v35, s101, v253
	v_med3_i32 v36, v36, s101, v253
	v_med3_i32 v37, v37, s101, v253
	v_med3_i32 v38, v38, s101, v253
	v_lshl_add_u32 v39, v39, 6, v252
	v_med3_i32 v39, v39, s101, v253
	v_mov_b32_e32 v65, v39
	ds_read_b32 v61, v34 offset:256
	ds_read_b32 v41, v35 offset:256
	ds_read_b32 v40, v36 offset:256
	ds_read_b32 v39, v37 offset:256
	ds_read_b32 v38, v38 offset:256
	ds_read_b32 v37, v63 offset:256
	ds_read_b32 v36, v64 offset:256
	ds_read_b32 v35, v65 offset:256
	s_waitcnt lgkmcnt(7)
	v_fmac_f32_e32 v61, 0x3fb8aa3b, v42
	s_waitcnt lgkmcnt(6)
	v_fmac_f32_e32 v41, 0x3fb8aa3b, v43
	v_max3_f32 v33, v33, v61, v41
	s_waitcnt lgkmcnt(5)
	v_fmac_f32_e32 v40, 0x3fb8aa3b, v44
	s_waitcnt lgkmcnt(4)
	v_fmac_f32_e32 v39, 0x3fb8aa3b, v45
	v_max3_f32 v33, v33, v40, v39
	s_waitcnt lgkmcnt(3)
	v_fmac_f32_e32 v38, 0x3fb8aa3b, v46
	s_waitcnt lgkmcnt(2)
	v_fmac_f32_e32 v37, 0x3fb8aa3b, v47
	v_max3_f32 v33, v33, v38, v37
	s_waitcnt lgkmcnt(1)
	v_fmac_f32_e32 v36, 0x3fb8aa3b, v48
	s_waitcnt lgkmcnt(0)
	v_fmac_f32_e32 v35, 0x3fb8aa3b, v49
	v_max3_f32 v33, v33, v36, v35
	ds_bpermute_b32 v34, v155, v33
	s_waitcnt lgkmcnt(0)
	v_max3_f32 v48, v68, v33, v34
	v_cmp_neq_f32_e32 vcc, s70, v48
	s_nop 1
	v_cndmask_b32_e32 v33, 0, v48, vcc
	v_sub_f32_e32 v34, v68, v33
	v_exp_f32_e32 v34, v34
	s_nop 0
	v_cmp_neq_f32_e32 vcc, 1.0, v34
	s_cbranch_vccz .LBB0_1287
	v_mul_f32_e32 v30, v30, v34
	v_mul_f32_e32 v31, v31, v34
	v_mul_f32_e32 v28, v28, v34
	v_mul_f32_e32 v29, v29, v34
	v_mul_f32_e32 v26, v26, v34
	v_mul_f32_e32 v27, v27, v34
	v_mul_f32_e32 v24, v24, v34
	v_mul_f32_e32 v25, v25, v34
	v_mul_f32_e32 v22, v22, v34
	v_mul_f32_e32 v23, v23, v34
	v_mul_f32_e32 v20, v20, v34
	v_mul_f32_e32 v21, v21, v34
	v_mul_f32_e32 v18, v18, v34
	v_mul_f32_e32 v19, v19, v34
	v_mul_f32_e32 v16, v16, v34
	v_mul_f32_e32 v17, v17, v34
	v_mul_f32_e32 v14, v14, v34
	v_mul_f32_e32 v15, v15, v34
	v_mul_f32_e32 v12, v12, v34
	v_mul_f32_e32 v13, v13, v34
	v_mul_f32_e32 v10, v10, v34
	v_mul_f32_e32 v11, v11, v34
	v_mul_f32_e32 v8, v8, v34
	v_mul_f32_e32 v9, v9, v34
	v_mul_f32_e32 v6, v6, v34
	v_mul_f32_e32 v7, v7, v34
	v_mul_f32_e32 v4, v4, v34
	v_mul_f32_e32 v5, v5, v34
	v_mul_f32_e32 v2, v2, v34
	v_mul_f32_e32 v3, v3, v34
	v_mul_f32_e32 v0, v0, v34
	v_mul_f32_e32 v1, v1, v34

.LBB0_1291:
	s_mul_i32 s3, s2, 0x2400
	v_add_u32_e32 v8, s3, v156
	v_add_u32_e32 v9, v8, v157
	ds_read_b128 v[0:3], v9
	ds_read_b128 v[4:7], v9 offset:32
	s_lshl_b32 s2, s2, 6
	v_subrev_u32_e32 v10, s2, v159
	v_xad_u32 v11, s2, -1, v159
	s_waitcnt lgkmcnt(1)
	v_mfma_f32_32x32x16_bf16 v[16:31], v[0:3], v[80:83], 0
	ds_read_b128 v[0:3], v9 offset:64
	v_subrev_u32_e32 v12, s2, v160
	v_subrev_u32_e32 v13, s2, v161
	v_add_u32_e32 v8, v8, v158
	v_lshl_add_u32 v10, v10, 6, v252
	v_lshl_add_u32 v11, v11, 6, v252
	v_lshl_add_u32 v12, v12, 6, v252
	s_waitcnt lgkmcnt(1)
	v_mfma_f32_32x32x16_bf16 v[16:31], v[4:7], v[84:87], v[16:31]
	ds_read_b128 v[4:7], v9 offset:96
	v_lshl_add_u32 v9, v13, 6, v252
	v_subrev_u32_e32 v14, s2, v162
	v_lshl_add_u32 v48, v14, 6, v252
	v_subrev_u32_e32 v54, s2, v164
	v_subrev_u32_e32 v53, s2, v163
	v_lshl_add_u32 v53, v53, 6, v252
	s_waitcnt lgkmcnt(1)
	v_mfma_f32_32x32x16_bf16 v[16:31], v[0:3], v[88:91], v[16:31]
	ds_read_b128 v[0:3], v8
	ds_read_b128 v[36:39], v8 offset:32
	ds_read_b128 v[40:43], v8 offset:64
	ds_read_b128 v[44:47], v8 offset:96
	v_med3_i32 v8, v10, s101, v253
	v_mov_b32_e32 v49, v8
	v_med3_i32 v48, v48, s101, v253
	v_med3_i32 v53, v53, s101, v253
	s_waitcnt lgkmcnt(4)
	v_mfma_f32_32x32x16_bf16 v[16:31], v[4:7], v[92:95], v[16:31]
	v_med3_i32 v4, v11, s101, v253
	v_med3_i32 v5, v12, s101, v253
	v_med3_i32 v6, v9, s101, v253
	v_mov_b32_e32 v50, v4
	v_mov_b32_e32 v51, v5
	v_mov_b32_e32 v52, v6
	s_waitcnt lgkmcnt(3)
	v_mfma_f32_32x32x16_bf16 v[0:15], v[0:3], v[80:83], 0
	s_waitcnt lgkmcnt(2)
	v_mfma_f32_32x32x16_bf16 v[0:15], v[36:39], v[84:87], v[0:15]
	v_subrev_u32_e32 v37, s2, v165
	v_lshl_add_u32 v36, v54, 6, v252
	v_lshl_add_u32 v37, v37, 6, v252
	v_med3_i32 v36, v36, s101, v253
	v_med3_i32 v37, v37, s101, v253
	s_waitcnt lgkmcnt(1)
	v_mfma_f32_32x32x16_bf16 v[0:15], v[40:43], v[88:91], v[0:15]
	ds_read_b32 v38, v49 offset:256
	ds_read_b32 v39, v50 offset:256
	ds_read_b32 v40, v51 offset:256
	ds_read_b32 v41, v52 offset:256
	ds_read_b32 v42, v48 offset:256
	ds_read_b32 v43, v53 offset:256
	ds_read_b32 v36, v36 offset:256
	ds_read_b32 v37, v37 offset:256
	s_waitcnt lgkmcnt(8)
	v_mfma_f32_32x32x16_bf16 v[0:15], v[44:47], v[92:95], v[0:15]
	s_waitcnt lgkmcnt(7)
	v_fmac_f32_e32 v38, 0x3fb8aa3b, v16
	s_waitcnt lgkmcnt(6)
	v_fmac_f32_e32 v39, 0x3fb8aa3b, v17
	s_waitcnt lgkmcnt(5)
	v_fmac_f32_e32 v40, 0x3fb8aa3b, v18
	s_waitcnt lgkmcnt(4)
	v_fmac_f32_e32 v41, 0x3fb8aa3b, v19
	s_waitcnt lgkmcnt(3)
	v_fmac_f32_e32 v42, 0x3fb8aa3b, v20
	s_waitcnt lgkmcnt(2)
	v_fmac_f32_e32 v43, 0x3fb8aa3b, v21
	s_waitcnt lgkmcnt(1)
	v_fmac_f32_e32 v36, 0x3fb8aa3b, v22
	s_waitcnt lgkmcnt(0)
	v_fmac_f32_e32 v37, 0x3fb8aa3b, v23
	v_subrev_u32_e32 v16, s2, v166
	v_subrev_u32_e32 v17, s2, v167
	v_subrev_u32_e32 v18, s2, v168
	v_subrev_u32_e32 v19, s2, v169
	v_subrev_u32_e32 v20, s2, v170
	v_subrev_u32_e32 v21, s2, v171
	v_subrev_u32_e32 v22, s2, v172
	v_subrev_u32_e32 v23, s2, v173
	v_lshl_add_u32 v16, v16, 6, v252
	v_lshl_add_u32 v17, v17, 6, v252
	v_lshl_add_u32 v18, v18, 6, v252
	v_lshl_add_u32 v19, v19, 6, v252
	v_lshl_add_u32 v20, v20, 6, v252
	v_lshl_add_u32 v21, v21, 6, v252
	v_lshl_add_u32 v22, v22, 6, v252
	v_lshl_add_u32 v23, v23, 6, v252
	v_med3_i32 v16, v16, s101, v253
	v_med3_i32 v17, v17, s101, v253
	v_med3_i32 v18, v18, s101, v253
	v_med3_i32 v19, v19, s101, v253
	v_med3_i32 v20, v20, s101, v253
	v_med3_i32 v21, v21, s101, v253
	v_med3_i32 v22, v22, s101, v253
	v_med3_i32 v23, v23, s101, v253
	ds_read_b32 v16, v16 offset:256
	ds_read_b32 v17, v17 offset:256
	ds_read_b32 v18, v18 offset:256
	ds_read_b32 v19, v19 offset:256
	ds_read_b32 v20, v20 offset:256
	ds_read_b32 v21, v21 offset:256
	ds_read_b32 v22, v22 offset:256
	ds_read_b32 v23, v23 offset:256
	s_waitcnt lgkmcnt(7)
	v_fmac_f32_e32 v16, 0x3fb8aa3b, v24
	s_waitcnt lgkmcnt(6)
	v_fmac_f32_e32 v17, 0x3fb8aa3b, v25
	s_waitcnt lgkmcnt(5)
	v_fmac_f32_e32 v18, 0x3fb8aa3b, v26
	s_waitcnt lgkmcnt(4)
	v_fmac_f32_e32 v19, 0x3fb8aa3b, v27
	s_waitcnt lgkmcnt(3)
	v_fmac_f32_e32 v20, 0x3fb8aa3b, v28
	s_waitcnt lgkmcnt(2)
	v_fmac_f32_e32 v21, 0x3fb8aa3b, v29
	s_waitcnt lgkmcnt(1)
	v_fmac_f32_e32 v22, 0x3fb8aa3b, v30
	s_waitcnt lgkmcnt(0)
	v_fmac_f32_e32 v23, 0x3fb8aa3b, v31
	v_subrev_u32_e32 v24, s2, v174
	v_subrev_u32_e32 v25, s2, v175
	v_subrev_u32_e32 v26, s2, v176
	v_subrev_u32_e32 v27, s2, v177
	v_subrev_u32_e32 v28, s2, v178
	v_subrev_u32_e32 v29, s2, v179
	v_subrev_u32_e32 v30, s2, v180
	v_subrev_u32_e32 v31, s2, v181
	v_lshl_add_u32 v24, v24, 6, v252
	v_lshl_add_u32 v25, v25, 6, v252
	v_lshl_add_u32 v26, v26, 6, v252
	v_lshl_add_u32 v27, v27, 6, v252
	v_lshl_add_u32 v28, v28, 6, v252
	v_lshl_add_u32 v29, v29, 6, v252
	v_lshl_add_u32 v30, v30, 6, v252
	v_lshl_add_u32 v31, v31, 6, v252
	v_med3_i32 v24, v24, s101, v253
	v_med3_i32 v25, v25, s101, v253
	v_med3_i32 v26, v26, s101, v253
	v_med3_i32 v27, v27, s101, v253
	v_med3_i32 v28, v28, s101, v253
	v_med3_i32 v29, v29, s101, v253
	v_med3_i32 v30, v30, s101, v253
	v_med3_i32 v31, v31, s101, v253
	ds_read_b32 v24, v24 offset:256
	ds_read_b32 v25, v25 offset:256
	ds_read_b32 v26, v26 offset:256
	ds_read_b32 v27, v27 offset:256
	ds_read_b32 v28, v28 offset:256
	ds_read_b32 v29, v29 offset:256
	ds_read_b32 v30, v30 offset:256
	ds_read_b32 v31, v31 offset:256
	s_waitcnt lgkmcnt(7)
	v_fmac_f32_e32 v24, 0x3fb8aa3b, v0
	s_waitcnt lgkmcnt(6)
	v_fmac_f32_e32 v25, 0x3fb8aa3b, v1
	s_waitcnt lgkmcnt(5)
	v_fmac_f32_e32 v26, 0x3fb8aa3b, v2
	s_waitcnt lgkmcnt(4)
	v_fmac_f32_e32 v27, 0x3fb8aa3b, v3
	s_waitcnt lgkmcnt(3)
	v_fmac_f32_e32 v28, 0x3fb8aa3b, v4
	s_waitcnt lgkmcnt(2)
	v_fmac_f32_e32 v29, 0x3fb8aa3b, v5
	s_waitcnt lgkmcnt(1)
	v_fmac_f32_e32 v30, 0x3fb8aa3b, v6
	s_waitcnt lgkmcnt(0)
	v_fmac_f32_e32 v31, 0x3fb8aa3b, v7
	v_subrev_u32_e32 v0, s2, v182
	v_subrev_u32_e32 v1, s2, v183
	v_subrev_u32_e32 v2, s2, v184
	v_subrev_u32_e32 v3, s2, v185
	v_subrev_u32_e32 v4, s2, v186
	v_subrev_u32_e32 v5, s2, v187
	v_subrev_u32_e32 v6, s2, v189
	v_subrev_u32_e32 v7, s2, v190
	v_lshl_add_u32 v0, v0, 6, v252
	v_lshl_add_u32 v1, v1, 6, v252
	v_lshl_add_u32 v2, v2, 6, v252
	v_lshl_add_u32 v3, v3, 6, v252
	v_lshl_add_u32 v4, v4, 6, v252
	v_lshl_add_u32 v5, v5, 6, v252
	v_lshl_add_u32 v6, v6, 6, v252
	v_lshl_add_u32 v7, v7, 6, v252
	v_med3_i32 v0, v0, s101, v253
	v_med3_i32 v1, v1, s101, v253
	v_med3_i32 v2, v2, s101, v253
	v_med3_i32 v3, v3, s101, v253
	v_med3_i32 v4, v4, s101, v253
	v_med3_i32 v5, v5, s101, v253
	v_med3_i32 v6, v6, s101, v253
	v_med3_i32 v7, v7, s101, v253
	ds_read_b32 v0, v0 offset:256
	ds_read_b32 v1, v1 offset:256
	ds_read_b32 v2, v2 offset:256
	ds_read_b32 v3, v3 offset:256
	ds_read_b32 v4, v4 offset:256
	ds_read_b32 v5, v5 offset:256
	ds_read_b32 v6, v6 offset:256
	ds_read_b32 v7, v7 offset:256
	s_waitcnt lgkmcnt(7)
	v_fmac_f32_e32 v0, 0x3fb8aa3b, v8
	s_waitcnt lgkmcnt(6)
	v_fmac_f32_e32 v1, 0x3fb8aa3b, v9
	s_waitcnt lgkmcnt(5)
	v_fmac_f32_e32 v2, 0x3fb8aa3b, v10
	s_waitcnt lgkmcnt(4)
	v_fmac_f32_e32 v3, 0x3fb8aa3b, v11
	s_waitcnt lgkmcnt(3)
	v_fmac_f32_e32 v4, 0x3fb8aa3b, v12
	s_waitcnt lgkmcnt(2)
	v_fmac_f32_e32 v5, 0x3fb8aa3b, v13
	s_waitcnt lgkmcnt(1)
	v_fmac_f32_e32 v6, 0x3fb8aa3b, v14
	s_waitcnt lgkmcnt(0)
	v_fmac_f32_e32 v7, 0x3fb8aa3b, v15
	v_sub_f32_e32 v12, v41, v33
	v_exp_f32_e32 v12, v12
	v_sub_f32_e32 v10, v39, v33
	v_sub_f32_e32 v15, v36, v33
	v_sub_f32_e32 v36, v37, v33
	v_sub_f32_e32 v9, v38, v33
	v_sub_f32_e32 v14, v43, v33
	v_sub_f32_e32 v17, v17, v33
	v_sub_f32_e32 v19, v19, v33
	v_sub_f32_e32 v23, v23, v33
	v_sub_f32_e32 v27, v27, v33
	v_sub_f32_e32 v31, v31, v33
	v_sub_f32_e32 v1, v1, v33
	v_sub_f32_e32 v3, v3, v33
	v_exp_f32_e32 v10, v10
	v_exp_f32_e32 v36, v36
	v_sub_f32_e32 v11, v40, v33
	v_sub_f32_e32 v13, v42, v33
	v_sub_f32_e32 v16, v16, v33
	v_sub_f32_e32 v18, v18, v33
	v_sub_f32_e32 v0, v0, v33
	v_sub_f32_e32 v2, v2, v33
	v_sub_f32_e32 v7, v7, v33
	v_exp_f32_e32 v9, v9
	v_exp_f32_e32 v14, v14
	v_exp_f32_e32 v17, v17
	v_exp_f32_e32 v19, v19
	v_exp_f32_e32 v23, v23
	v_exp_f32_e32 v27, v27
	v_exp_f32_e32 v31, v31
	v_exp_f32_e32 v1, v1
	v_exp_f32_e32 v3, v3
	v_mul_f32_e32 v12, v34, v12
	v_exp_f32_e32 v11, v11
	v_exp_f32_e32 v13, v13
	v_exp_f32_e32 v15, v15
	v_exp_f32_e32 v16, v16
	v_exp_f32_e32 v18, v18
	v_exp_f32_e32 v0, v0
	v_exp_f32_e32 v2, v2
	v_exp_f32_e32 v7, v7
	ds_bpermute_b32 v37, v155, v12
	v_sub_f32_e32 v21, v21, v33
	v_sub_f32_e32 v25, v25, v33
	v_sub_f32_e32 v29, v29, v33
	v_sub_f32_e32 v5, v5, v33
	v_mul_f32_e32 v10, v34, v10
	v_mul_f32_e32 v36, v34, v36
	v_sub_f32_e32 v20, v20, v33
	v_sub_f32_e32 v22, v22, v33
	v_sub_f32_e32 v24, v24, v33
	v_sub_f32_e32 v26, v26, v33
	v_sub_f32_e32 v28, v28, v33
	v_sub_f32_e32 v30, v30, v33
	v_sub_f32_e32 v4, v4, v33
	v_exp_f32_e32 v21, v21
	v_exp_f32_e32 v25, v25
	v_exp_f32_e32 v29, v29
	v_exp_f32_e32 v5, v5
	v_mul_f32_e32 v14, v34, v14
	v_mul_f32_e32 v17, v34, v17
	v_mul_f32_e32 v19, v34, v19
	v_mul_f32_e32 v23, v34, v23
	v_mul_f32_e32 v27, v34, v27
	v_mul_f32_e32 v31, v34, v31
	v_mul_f32_e32 v1, v34, v1
	v_mul_f32_e32 v3, v34, v3
	v_fmac_f32_e32 v10, v34, v9
	ds_bpermute_b32 v9, v155, v36
	v_sub_f32_e32 v6, v6, v33
	v_exp_f32_e32 v20, v20
	v_exp_f32_e32 v22, v22
	v_exp_f32_e32 v24, v24
	v_exp_f32_e32 v26, v26
	v_exp_f32_e32 v28, v28
	v_exp_f32_e32 v30, v30
	v_exp_f32_e32 v4, v4
	v_mul_f32_e32 v7, v34, v7
	v_fmac_f32_e32 v12, v34, v11
	v_fmac_f32_e32 v14, v34, v13
	v_fmac_f32_e32 v36, v34, v15
	ds_bpermute_b32 v11, v155, v19
	v_fmac_f32_e32 v17, v34, v16
	v_fmac_f32_e32 v19, v34, v18
	ds_bpermute_b32 v13, v155, v23
	ds_bpermute_b32 v15, v155, v27
	ds_bpermute_b32 v16, v155, v31
	ds_bpermute_b32 v18, v155, v3
	v_fmac_f32_e32 v1, v34, v0
	v_fmac_f32_e32 v3, v34, v2
	v_exp_f32_e32 v6, v6
	v_add_f32_e32 v1, v1, v3
	s_waitcnt lgkmcnt(6)
	v_cndmask_b32_e64 v3, v37, v35, s[4:5]
	ds_bpermute_b32 v35, v155, v7
	v_mul_f32_e32 v21, v34, v21
	v_mul_f32_e32 v25, v34, v25
	v_mul_f32_e32 v29, v34, v29
	v_mul_f32_e32 v5, v34, v5
	v_add_u32_e32 v8, s2, v110
	v_fmac_f32_e32 v21, v34, v20
	v_fmac_f32_e32 v23, v34, v22
	v_fmac_f32_e32 v25, v34, v24
	v_fmac_f32_e32 v27, v34, v26
	v_fmac_f32_e32 v29, v34, v28
	v_fmac_f32_e32 v31, v34, v30
	v_fmac_f32_e32 v5, v34, v4
	v_add_f32_e32 v0, v10, v12
	v_add_f32_e32 v2, v14, v36
	v_add_f32_e32 v4, v17, v19
	s_waitcnt lgkmcnt(6)
	v_cndmask_b32_e64 v17, v9, v37, s[4:5]
	v_add_u32_e32 v8, 0x9000, v8
	v_add_f32_e32 v10, v21, v23
	v_add_f32_e32 v12, v25, v27
	v_add_f32_e32 v14, v29, v31
	s_waitcnt lgkmcnt(5)
	v_cndmask_b32_e64 v9, v11, v9, s[4:5]
	s_waitcnt lgkmcnt(4)
	v_cndmask_b32_e64 v11, v13, v11, s[4:5]
	s_waitcnt lgkmcnt(3)
	v_cndmask_b32_e64 v13, v15, v13, s[4:5]
	s_waitcnt lgkmcnt(2)
	v_cndmask_b32_e64 v15, v16, v15, s[4:5]
	v_fmac_f32_e32 v7, v34, v6
	v_add_f32_e32 v0, v0, v3
	v_add_f32_e32 v2, v2, v17
	s_waitcnt lgkmcnt(1)
	v_cndmask_b32_e64 v16, v18, v16, s[4:5]
	v_add_f32_e32 v3, v4, v9
	v_add_f32_e32 v4, v10, v11
	v_add_f32_e32 v6, v12, v13
	v_add_f32_e32 v9, v14, v15
	v_add_f32_e32 v5, v5, v7
	ds_write2_b32 v8, v0, v2 offset1:2
	ds_write2_b32 v8, v3, v4 offset0:4 offset1:6
	ds_write2_b32 v8, v6, v9 offset0:8 offset1:10
	s_waitcnt lgkmcnt(3)
	v_cndmask_b32_e64 v0, v35, v18, s[4:5]
	s_mov_b32 s2, 1
	s_and_b64 vcc, exec, s[30:31]
	s_mov_b64 s[30:31], 0
	v_add_f32_e32 v1, v1, v16
	v_add_f32_e32 v0, v5, v0
	ds_write2_b32 v8, v1, v0 offset0:12 offset1:14
	s_cbranch_vccnz .LBB0_1291
